# W_up f32->bf16 transposition (4096 items) moved out of the HBM-bound P0 prologue into the memory-bound half of P2 where it overlaps other CUs' ssd_states; hand-written 2-item-per-wave loop, same math
# speedup vs baseline: 1.0049x; 1.0018x over previous
.LBB0_17:
	s_load_dwordx16 s[4:19], s[0:1], 0x40
	s_cmp_lt_i32 s86, 1
	v_lshrrev_b32_e32 v159, 6, v158
	s_waitcnt lgkmcnt(0)
	v_writelane_b32 v252, s4, 7
	s_nop 1
	v_writelane_b32 v252, s5, 8
	v_writelane_b32 v252, s6, 9
	v_writelane_b32 v252, s7, 10
	v_writelane_b32 v252, s8, 11
	v_writelane_b32 v252, s9, 12
	v_writelane_b32 v252, s10, 13
	v_writelane_b32 v252, s11, 14
	v_writelane_b32 v252, s12, 15
	v_writelane_b32 v252, s13, 16
	v_writelane_b32 v252, s14, 17
	v_writelane_b32 v252, s15, 18
	v_writelane_b32 v252, s16, 19
	v_writelane_b32 v252, s17, 20
	v_writelane_b32 v252, s18, 21
	v_writelane_b32 v252, s19, 22
	s_load_dwordx16 s[4:19], s[0:1], 0x80
	s_cselect_b64 s[0:1], -1, 0
	s_cmp_gt_i32 s87, 0
	s_cselect_b64 s[2:3], -1, 0
	s_and_b64 s[0:1], s[0:1], s[2:3]
	s_waitcnt lgkmcnt(0)
	v_writelane_b32 v252, s4, 23
	s_andn2_b64 vcc, exec, s[0:1]
	s_nop 0
	v_writelane_b32 v252, s5, 24
	v_writelane_b32 v252, s6, 25
	v_writelane_b32 v252, s7, 26
	v_writelane_b32 v252, s8, 27
	v_writelane_b32 v252, s9, 28
	v_writelane_b32 v252, s10, 29
	v_writelane_b32 v252, s11, 30
	v_writelane_b32 v252, s12, 31
	v_writelane_b32 v252, s13, 32
	v_writelane_b32 v252, s14, 33
	v_writelane_b32 v252, s15, 34
	v_writelane_b32 v252, s16, 35
	v_writelane_b32 v252, s17, 36
	v_writelane_b32 v252, s18, 37
	v_writelane_b32 v252, s19, 38
	s_cbranch_vccnz .LBB0_264
	v_lshrrev_b32_e32 v0, 6, v158
	v_lshl_add_u32 v64, s33, 3, v0
	s_movk_i32 s0, 0x23ff
	s_cmpk_lg_u32 s88, 0x100
	s_cbranch_scc1 .Lmy_p0b_0
	s_movk_i32 s0, 0x13ff
.Lmy_p0b_0:
	v_cmp_lt_i32_e32 vcc, s0, v64
	s_and_saveexec_b64 s[0:1], vcc
	s_xor_b64 s[0:1], exec, s[0:1]
	s_lshl_b32 s2, s33, 9
	s_or_saveexec_b64 s[4:5], s[0:1]
	v_and_b32_e32 v93, 63, v158
	s_lshl_b32 s12, s88, 3
	v_mov_b32_e32 v1, s2
	s_xor_b64 exec, exec, s[4:5]
	s_cbranch_execz .LBB0_186
	s_movk_i32 s0, 0x4100
	v_mad_u32_u24 v1, v0, s0, 0
	v_lshrrev_b32_e32 v66, 4, v93
	s_movk_i32 s0, 0x104
	v_mov_b32_e32 v3, 0x410
	v_mad_u32_u24 v102, v66, s0, v3
	v_mov_b32_e32 v3, 0x820
	v_mad_u32_u24 v103, v66, s0, v3
	v_mov_b32_e32 v3, 0xc30
	v_mad_u32_u24 v104, v66, s0, v3
	v_mov_b32_e32 v3, 0x1040
	v_mad_u32_u24 v105, v66, s0, v3
	v_mov_b32_e32 v3, 0x1450
	v_mad_u32_u24 v106, v66, s0, v3
	v_mov_b32_e32 v3, 0x1860
	v_mad_u32_u24 v107, v66, s0, v3
	v_mov_b32_e32 v3, 0x1c70
	v_mad_u32_u24 v108, v66, s0, v3
	v_mov_b32_e32 v3, 0x2080
	v_mad_u32_u24 v109, v66, s0, v3
	v_mov_b32_e32 v3, 0x2490
	v_mad_u32_u24 v110, v66, s0, v3
	v_mov_b32_e32 v3, 0x28a0
	v_mad_u32_u24 v111, v66, s0, v3
	v_mov_b32_e32 v3, 0x2cb0
	v_lshlrev_b32_e32 v2, 4, v158
	v_mad_u32_u24 v112, v66, s0, v3
	v_lshlrev_b32_e32 v3, 3, v158
	v_and_b32_e32 v2, 0xf0, v2
	v_and_b32_e32 v3, 56, v3
	v_add_u32_e32 v65, v1, v2
	v_lshlrev_b32_e32 v4, 1, v3
	v_mov_b32_e32 v5, 0
	v_readlane_b32 s64, v252, 7
	v_mad_u32_u24 v95, v66, s0, v65
	v_lshl_add_u64 v[68:69], s[84:85], 0, v[4:5]
	s_mov_b64 s[0:1], 0x5c00000
	v_readlane_b32 s78, v252, 21
	v_readlane_b32 s79, v252, 22
	v_readlane_b32 s16, v252, 23
	s_cmp_lg_u64 s[54:55], 0
	v_lshl_add_u64 v[70:71], v[68:69], 0, s[0:1]
	s_mov_b64 s[0:1], 0x800000
	v_readlane_b32 s17, v252, 24
	s_cselect_b64 s[6:7], -1, 0
	s_cmp_lg_u64 s[78:79], 0
	v_lshrrev_b32_e32 v113, 3, v93
	v_and_b32_e32 v254, 3, v113
	v_and_b32_e32 v255, 4, v113
	v_lshl_or_b32 v254, v255, 2, v254
	v_lshl_add_u64 v[72:73], v[68:69], 0, s[0:1]
	s_mov_b64 s[0:1], 0xa00000
	v_readlane_b32 s28, v252, 35
	v_readlane_b32 s29, v252, 36
	s_cselect_b64 s[8:9], -1, 0
	s_cmp_lg_u64 s[16:17], 0
	v_mul_u32_u24_e32 v6, 0x104, v3
	v_lshlrev_b32_e32 v3, 2, v113
	v_lshl_add_u64 v[74:75], v[68:69], 0, s[0:1]
	s_mov_b64 s[0:1], 0xe00000
	s_cselect_b64 s[10:11], -1, 0
	s_cmp_lg_u64 s[28:29], 0
	v_add3_u32 v114, v1, v6, v3
	v_lshl_add_u64 v[76:77], v[68:69], 0, s[0:1]
	s_mov_b64 s[0:1], 0x1000000
	v_mov_b32_e32 v3, v5
	v_readlane_b32 s76, v252, 19
	v_readlane_b32 s77, v252, 20
	v_readlane_b32 s18, v252, 25
	v_readlane_b32 s19, v252, 26
	v_readlane_b32 s20, v252, 27
	v_readlane_b32 s21, v252, 28
	v_readlane_b32 s24, v252, 31
	v_readlane_b32 s25, v252, 32
	v_readlane_b32 s26, v252, 33
	v_readlane_b32 s27, v252, 34
	v_readlane_b32 s30, v252, 37
	v_readlane_b32 s31, v252, 38
	s_cselect_b64 s[14:15], -1, 0
	s_lshl_b32 s13, s33, 9
	v_or_b32_e32 v115, 8, v113
	v_or_b32_e32 v116, 16, v113
	v_or_b32_e32 v117, 24, v113
	v_or_b32_e32 v118, 32, v113
	v_or_b32_e32 v119, 40, v113
	v_or_b32_e32 v120, 48, v113
	v_or_b32_e32 v121, 56, v113
	v_lshl_add_u64 v[78:79], v[68:69], 0, s[0:1]
	v_lshl_add_u64 v[80:81], s[56:57], 0, v[2:3]
	v_lshl_add_u64 v[82:83], s[76:77], 0, v[2:3]
	v_lshl_add_u64 v[84:85], s[18:19], 0, v[2:3]
	v_lshl_add_u64 v[86:87], s[20:21], 0, v[2:3]
	v_lshl_add_u64 v[88:89], s[26:27], 0, v[2:3]
	v_lshl_add_u64 v[90:91], s[30:31], 0, v[2:3]
	v_mov_b32_e32 v67, v5
	v_lshl_add_u32 v92, v0, 6, s13
	s_lshl_b32 s24, s12, 6
	s_movk_i32 s25, 0xbff
	s_mov_b32 s26, 0x2aaaaaab
	s_movk_i32 s27, 0xffa0
	s_movk_i32 s28, 0xe800
	s_movk_i32 s29, 0x6040
	s_movk_i32 s30, 0x3ff
	s_movk_i32 s31, 0xff
	v_mov_b32_e32 v122, 0x400
	v_mov_b32_e32 v94, v64
	s_movk_i32 s34, 0x1ff
	s_movk_i32 s35, 0x23ff
	s_cmpk_lg_u32 s88, 0x100
	s_cbranch_scc1 .Lmy_p0b_1
	s_movk_i32 s35, 0x13ff
.Lmy_p0b_1:
	s_mov_b64 s[16:17], 0
	v_readlane_b32 s65, v252, 8
	v_readlane_b32 s66, v252, 9
	v_readlane_b32 s67, v252, 10
	v_readlane_b32 s68, v252, 11
	v_readlane_b32 s69, v252, 12
	v_readlane_b32 s70, v252, 13
	v_readlane_b32 s71, v252, 14
	v_readlane_b32 s72, v252, 15
	v_readlane_b32 s73, v252, 16
	v_readlane_b32 s74, v252, 17
	v_readlane_b32 s75, v252, 18
	v_readlane_b32 s22, v252, 29
	v_readlane_b32 s23, v252, 30
	s_branch .LBB0_25

.Lmy_wup_begin:
	s_cmpk_lg_u32 s88, 0x100
	s_cbranch_scc1 .Lmy_wup_end
	s_waitcnt lgkmcnt(0)
	s_barrier
	v_readlane_b32 s2, v252, 0
	v_readlane_b32 s3, v252, 1
	s_add_u32 s2, s2, 0xffffff20
	s_addc_u32 s3, s3, -1
	s_load_dwordx4 s[4:7], s[2:3], 0xb0
	v_and_b32_e32 v197, 63, v158
	v_lshrrev_b32_e32 v198, 4, v197
	v_and_b32_e32 v194, 15, v197
	v_lshlrev_b32_e32 v194, 2, v194
	v_mul_u32_u24_e32 v193, 0x4100, v159
	v_mul_u32_u24_e32 v192, 65, v198
	v_add_u32_e32 v192, v192, v194
	v_lshl_add_u32 v176, v192, 2, v193
	v_add_u32_e32 v177, 0x410, v176
	v_add_u32_e32 v178, 0x820, v176
	v_add_u32_e32 v179, 0xc30, v176
	v_add_u32_e32 v180, 0x1040, v176
	v_add_u32_e32 v181, 0x1450, v176
	v_add_u32_e32 v182, 0x1860, v176
	v_add_u32_e32 v183, 0x1c70, v176
	v_add_u32_e32 v184, 0x2080, v176
	v_add_u32_e32 v185, 0x2490, v176
	v_add_u32_e32 v186, 0x28a0, v176
	v_add_u32_e32 v187, 0x2cb0, v176
	v_add_u32_e32 v188, 0x30c0, v176
	v_add_u32_e32 v189, 0x34d0, v176
	v_add_u32_e32 v190, 0x38e0, v176
	v_add_u32_e32 v191, 0x3cf0, v176
	v_lshlrev_b32_e32 v195, 2, v198
	v_lshlrev_b32_e32 v194, 2, v194
	v_lshl_add_u32 v194, v198, 15, v194
	v_and_b32_e32 v196, 7, v197
	v_mul_u32_u24_e32 v192, 0x208, v196
	v_lshrrev_b32_e32 v198, 3, v197
	v_add_u32_e32 v192, v192, v198
	v_lshl_add_u32 v192, v192, 2, v193
	v_add_u32_e32 v193, 0x400, v192
	v_lshlrev_b32_e32 v196, 4, v196
	v_lshl_add_u32 v196, v198, 12, v196
	v_readfirstlane_b32 s8, v159
	s_lshl_b32 s9, s33, 3
	s_add_i32 s8, s8, s9
	s_waitcnt lgkmcnt(0)
	s_lshr_b32 s9, s8, 7
	s_and_b32 s10, s8, 0x7f
	s_lshl_b32 s11, s9, 21
	s_lshl_b32 s12, s10, 8
	s_add_u32 s11, s11, s12
	s_add_u32 s16, s6, s11
	s_addc_u32 s17, s7, 0
	s_lshl_b32 s11, s9, 8
	s_add_u32 s18, s4, s11
	s_addc_u32 s19, s5, 0
	s_lshl_b32 s11, s10, 18
	s_lshl_b32 s12, s9, 7
	s_add_u32 s11, s11, s12
	s_add_u32 s11, s11, 0x1000000
	s_add_u32 s20, s84, s11
	s_addc_u32 s21, s85, 0
	s_addk_i32 s8, 0x800
	s_lshr_b32 s9, s8, 7
	s_and_b32 s10, s8, 0x7f
	s_lshl_b32 s11, s9, 21
	s_lshl_b32 s12, s10, 8
	s_add_u32 s11, s11, s12
	s_add_u32 s22, s6, s11
	s_addc_u32 s23, s7, 0
	s_lshl_b32 s11, s9, 8
	s_add_u32 s24, s4, s11
	s_addc_u32 s25, s5, 0
	s_lshl_b32 s11, s10, 18
	s_lshl_b32 s12, s9, 7
	s_add_u32 s11, s11, s12
	s_add_u32 s11, s11, 0x1000000
	s_add_u32 s26, s84, s11
	s_addc_u32 s27, s85, 0
	global_load_dword v128, v195, s[18:19]
	global_load_dword v129, v195, s[18:19] offset:16
	global_load_dword v130, v195, s[18:19] offset:32
	global_load_dword v131, v195, s[18:19] offset:48
	global_load_dword v132, v195, s[18:19] offset:64
	global_load_dword v133, v195, s[18:19] offset:80
	global_load_dword v134, v195, s[18:19] offset:96
	global_load_dword v135, v195, s[18:19] offset:112
	global_load_dword v136, v195, s[18:19] offset:128
	global_load_dword v137, v195, s[18:19] offset:144
	global_load_dword v138, v195, s[18:19] offset:160
	global_load_dword v139, v195, s[18:19] offset:176
	global_load_dword v140, v195, s[18:19] offset:192
	global_load_dword v141, v195, s[18:19] offset:208
	global_load_dword v142, v195, s[18:19] offset:224
	global_load_dword v143, v195, s[18:19] offset:240
	v_mov_b32_e32 v197, v194
	global_load_dwordx4 v[0:3], v197, s[16:17] nt
	v_add_u32_e32 v197, 0x20000, v197
	global_load_dwordx4 v[4:7], v197, s[16:17] nt
	v_add_u32_e32 v197, 0x20000, v197
	global_load_dwordx4 v[8:11], v197, s[16:17] nt
	v_add_u32_e32 v197, 0x20000, v197
	global_load_dwordx4 v[12:15], v197, s[16:17] nt
	v_add_u32_e32 v197, 0x20000, v197
	global_load_dwordx4 v[16:19], v197, s[16:17] nt
	v_add_u32_e32 v197, 0x20000, v197
	global_load_dwordx4 v[20:23], v197, s[16:17] nt
	v_add_u32_e32 v197, 0x20000, v197
	global_load_dwordx4 v[24:27], v197, s[16:17] nt
	v_add_u32_e32 v197, 0x20000, v197
	global_load_dwordx4 v[28:31], v197, s[16:17] nt
	v_add_u32_e32 v197, 0x20000, v197
	global_load_dwordx4 v[32:35], v197, s[16:17] nt
	v_add_u32_e32 v197, 0x20000, v197
	global_load_dwordx4 v[36:39], v197, s[16:17] nt
	v_add_u32_e32 v197, 0x20000, v197
	global_load_dwordx4 v[40:43], v197, s[16:17] nt
	v_add_u32_e32 v197, 0x20000, v197
	global_load_dwordx4 v[44:47], v197, s[16:17] nt
	v_add_u32_e32 v197, 0x20000, v197
	global_load_dwordx4 v[48:51], v197, s[16:17] nt
	v_add_u32_e32 v197, 0x20000, v197
	global_load_dwordx4 v[52:55], v197, s[16:17] nt
	v_add_u32_e32 v197, 0x20000, v197
	global_load_dwordx4 v[56:59], v197, s[16:17] nt
	v_add_u32_e32 v197, 0x20000, v197
	global_load_dwordx4 v[60:63], v197, s[16:17] nt
	global_load_dword v160, v195, s[24:25]
	global_load_dword v161, v195, s[24:25] offset:16
	global_load_dword v162, v195, s[24:25] offset:32
	global_load_dword v163, v195, s[24:25] offset:48
	global_load_dword v164, v195, s[24:25] offset:64
	global_load_dword v165, v195, s[24:25] offset:80
	global_load_dword v166, v195, s[24:25] offset:96
	global_load_dword v167, v195, s[24:25] offset:112
	global_load_dword v168, v195, s[24:25] offset:128
	global_load_dword v169, v195, s[24:25] offset:144
	global_load_dword v170, v195, s[24:25] offset:160
	global_load_dword v171, v195, s[24:25] offset:176
	global_load_dword v172, v195, s[24:25] offset:192
	global_load_dword v173, v195, s[24:25] offset:208
	global_load_dword v174, v195, s[24:25] offset:224
	global_load_dword v175, v195, s[24:25] offset:240
	v_mov_b32_e32 v197, v194
	global_load_dwordx4 v[64:67], v197, s[22:23] nt
	v_add_u32_e32 v197, 0x20000, v197
	global_load_dwordx4 v[68:71], v197, s[22:23] nt
	v_add_u32_e32 v197, 0x20000, v197
	global_load_dwordx4 v[72:75], v197, s[22:23] nt
	v_add_u32_e32 v197, 0x20000, v197
	global_load_dwordx4 v[76:79], v197, s[22:23] nt
	v_add_u32_e32 v197, 0x20000, v197
	global_load_dwordx4 v[80:83], v197, s[22:23] nt
	v_add_u32_e32 v197, 0x20000, v197
	global_load_dwordx4 v[84:87], v197, s[22:23] nt
	v_add_u32_e32 v197, 0x20000, v197
	global_load_dwordx4 v[88:91], v197, s[22:23] nt
	v_add_u32_e32 v197, 0x20000, v197
	global_load_dwordx4 v[92:95], v197, s[22:23] nt
	v_add_u32_e32 v197, 0x20000, v197
	global_load_dwordx4 v[96:99], v197, s[22:23] nt
	v_add_u32_e32 v197, 0x20000, v197
	global_load_dwordx4 v[100:103], v197, s[22:23] nt
	v_add_u32_e32 v197, 0x20000, v197
	global_load_dwordx4 v[104:107], v197, s[22:23] nt
	v_add_u32_e32 v197, 0x20000, v197
	global_load_dwordx4 v[108:111], v197, s[22:23] nt
	v_add_u32_e32 v197, 0x20000, v197
	global_load_dwordx4 v[112:115], v197, s[22:23] nt
	v_add_u32_e32 v197, 0x20000, v197
	global_load_dwordx4 v[116:119], v197, s[22:23] nt
	v_add_u32_e32 v197, 0x20000, v197
	global_load_dwordx4 v[120:123], v197, s[22:23] nt
	v_add_u32_e32 v197, 0x20000, v197
	global_load_dwordx4 v[124:127], v197, s[22:23] nt
	s_waitcnt vmcnt(47)
	v_mul_f32_e32 v0, v0, v128
	v_mul_f32_e32 v1, v1, v128
	v_mul_f32_e32 v2, v2, v128
	v_mul_f32_e32 v3, v3, v128
	ds_write2_b32 v176, v0, v1 offset1:1
	ds_write2_b32 v176, v2, v3 offset0:2 offset1:3
	s_waitcnt vmcnt(46)
	v_mul_f32_e32 v4, v4, v129
	v_mul_f32_e32 v5, v5, v129
	v_mul_f32_e32 v6, v6, v129
	v_mul_f32_e32 v7, v7, v129
	ds_write2_b32 v177, v4, v5 offset1:1
	ds_write2_b32 v177, v6, v7 offset0:2 offset1:3
	s_waitcnt vmcnt(45)
	v_mul_f32_e32 v8, v8, v130
	v_mul_f32_e32 v9, v9, v130
	v_mul_f32_e32 v10, v10, v130
	v_mul_f32_e32 v11, v11, v130
	ds_write2_b32 v178, v8, v9 offset1:1
	ds_write2_b32 v178, v10, v11 offset0:2 offset1:3
	s_waitcnt vmcnt(44)
	v_mul_f32_e32 v12, v12, v131
	v_mul_f32_e32 v13, v13, v131
	v_mul_f32_e32 v14, v14, v131
	v_mul_f32_e32 v15, v15, v131
	ds_write2_b32 v179, v12, v13 offset1:1
	ds_write2_b32 v179, v14, v15 offset0:2 offset1:3
	s_waitcnt vmcnt(43)
	v_mul_f32_e32 v16, v16, v132
	v_mul_f32_e32 v17, v17, v132
	v_mul_f32_e32 v18, v18, v132
	v_mul_f32_e32 v19, v19, v132
	ds_write2_b32 v180, v16, v17 offset1:1
	ds_write2_b32 v180, v18, v19 offset0:2 offset1:3
	s_waitcnt vmcnt(42)
	v_mul_f32_e32 v20, v20, v133
	v_mul_f32_e32 v21, v21, v133
	v_mul_f32_e32 v22, v22, v133
	v_mul_f32_e32 v23, v23, v133
	ds_write2_b32 v181, v20, v21 offset1:1
	ds_write2_b32 v181, v22, v23 offset0:2 offset1:3
	s_waitcnt vmcnt(41)
	v_mul_f32_e32 v24, v24, v134
	v_mul_f32_e32 v25, v25, v134
	v_mul_f32_e32 v26, v26, v134
	v_mul_f32_e32 v27, v27, v134
	ds_write2_b32 v182, v24, v25 offset1:1
	ds_write2_b32 v182, v26, v27 offset0:2 offset1:3
	s_waitcnt vmcnt(40)
	v_mul_f32_e32 v28, v28, v135
	v_mul_f32_e32 v29, v29, v135
	v_mul_f32_e32 v30, v30, v135
	v_mul_f32_e32 v31, v31, v135
	ds_write2_b32 v183, v28, v29 offset1:1
	ds_write2_b32 v183, v30, v31 offset0:2 offset1:3
	s_waitcnt vmcnt(39)
	v_mul_f32_e32 v32, v32, v136
	v_mul_f32_e32 v33, v33, v136
	v_mul_f32_e32 v34, v34, v136
	v_mul_f32_e32 v35, v35, v136
	ds_write2_b32 v184, v32, v33 offset1:1
	ds_write2_b32 v184, v34, v35 offset0:2 offset1:3
	s_waitcnt vmcnt(38)
	v_mul_f32_e32 v36, v36, v137
	v_mul_f32_e32 v37, v37, v137
	v_mul_f32_e32 v38, v38, v137
	v_mul_f32_e32 v39, v39, v137
	ds_write2_b32 v185, v36, v37 offset1:1
	ds_write2_b32 v185, v38, v39 offset0:2 offset1:3
	s_waitcnt vmcnt(37)
	v_mul_f32_e32 v40, v40, v138
	v_mul_f32_e32 v41, v41, v138
	v_mul_f32_e32 v42, v42, v138
	v_mul_f32_e32 v43, v43, v138
	ds_write2_b32 v186, v40, v41 offset1:1
	ds_write2_b32 v186, v42, v43 offset0:2 offset1:3
	s_waitcnt vmcnt(36)
	v_mul_f32_e32 v44, v44, v139
	v_mul_f32_e32 v45, v45, v139
	v_mul_f32_e32 v46, v46, v139
	v_mul_f32_e32 v47, v47, v139
	ds_write2_b32 v187, v44, v45 offset1:1
	ds_write2_b32 v187, v46, v47 offset0:2 offset1:3
	s_waitcnt vmcnt(35)
	v_mul_f32_e32 v48, v48, v140
	v_mul_f32_e32 v49, v49, v140
	v_mul_f32_e32 v50, v50, v140
	v_mul_f32_e32 v51, v51, v140
	ds_write2_b32 v188, v48, v49 offset1:1
	ds_write2_b32 v188, v50, v51 offset0:2 offset1:3
	s_waitcnt vmcnt(34)
	v_mul_f32_e32 v52, v52, v141
	v_mul_f32_e32 v53, v53, v141
	v_mul_f32_e32 v54, v54, v141
	v_mul_f32_e32 v55, v55, v141
	ds_write2_b32 v189, v52, v53 offset1:1
	ds_write2_b32 v189, v54, v55 offset0:2 offset1:3
	s_waitcnt vmcnt(33)
	v_mul_f32_e32 v56, v56, v142
	v_mul_f32_e32 v57, v57, v142
	v_mul_f32_e32 v58, v58, v142
	v_mul_f32_e32 v59, v59, v142
	ds_write2_b32 v190, v56, v57 offset1:1
	ds_write2_b32 v190, v58, v59 offset0:2 offset1:3
	s_waitcnt vmcnt(32)
	v_mul_f32_e32 v60, v60, v143
	v_mul_f32_e32 v61, v61, v143
	v_mul_f32_e32 v62, v62, v143
	v_mul_f32_e32 v63, v63, v143
	ds_write2_b32 v191, v60, v61 offset1:1
	ds_write2_b32 v191, v62, v63 offset0:2 offset1:3
	s_waitcnt lgkmcnt(0)
	v_mov_b32_e32 v197, v196
	ds_read2_b32 v[208:209], v192 offset0:0 offset1:65
	ds_read2_b32 v[210:211], v192 offset0:130 offset1:195
	ds_read2_b32 v[212:213], v193 offset0:4 offset1:69
	ds_read2_b32 v[214:215], v193 offset0:134 offset1:199
	ds_read2_b32 v[216:217], v192 offset0:8 offset1:73
	ds_read2_b32 v[218:219], v192 offset0:138 offset1:203
	ds_read2_b32 v[220:221], v193 offset0:12 offset1:77
	ds_read2_b32 v[222:223], v193 offset0:142 offset1:207
	s_waitcnt lgkmcnt(4)
	v_cvt_pk_bf16_f32 v200, v208, v209
	v_cvt_pk_bf16_f32 v201, v210, v211
	v_cvt_pk_bf16_f32 v202, v212, v213
	v_cvt_pk_bf16_f32 v203, v214, v215
	global_store_dwordx4 v197, v[200:203], s[20:21]
	v_add_u32_e32 v197, 0x8000, v197
	s_waitcnt lgkmcnt(0)
	v_cvt_pk_bf16_f32 v204, v216, v217
	v_cvt_pk_bf16_f32 v205, v218, v219
	v_cvt_pk_bf16_f32 v206, v220, v221
	v_cvt_pk_bf16_f32 v207, v222, v223
	global_store_dwordx4 v197, v[204:207], s[20:21]
	v_add_u32_e32 v197, 0x8000, v197
	ds_read2_b32 v[208:209], v192 offset0:16 offset1:81
	ds_read2_b32 v[210:211], v192 offset0:146 offset1:211
	ds_read2_b32 v[212:213], v193 offset0:20 offset1:85
	ds_read2_b32 v[214:215], v193 offset0:150 offset1:215
	ds_read2_b32 v[216:217], v192 offset0:24 offset1:89
	ds_read2_b32 v[218:219], v192 offset0:154 offset1:219
	ds_read2_b32 v[220:221], v193 offset0:28 offset1:93
	ds_read2_b32 v[222:223], v193 offset0:158 offset1:223
	s_waitcnt lgkmcnt(4)
	v_cvt_pk_bf16_f32 v200, v208, v209
	v_cvt_pk_bf16_f32 v201, v210, v211
	v_cvt_pk_bf16_f32 v202, v212, v213
	v_cvt_pk_bf16_f32 v203, v214, v215
	global_store_dwordx4 v197, v[200:203], s[20:21]
	v_add_u32_e32 v197, 0x8000, v197
	s_waitcnt lgkmcnt(0)
	v_cvt_pk_bf16_f32 v204, v216, v217
	v_cvt_pk_bf16_f32 v205, v218, v219
	v_cvt_pk_bf16_f32 v206, v220, v221
	v_cvt_pk_bf16_f32 v207, v222, v223
	global_store_dwordx4 v197, v[204:207], s[20:21]
	v_add_u32_e32 v197, 0x8000, v197
	ds_read2_b32 v[208:209], v192 offset0:32 offset1:97
	ds_read2_b32 v[210:211], v192 offset0:162 offset1:227
	ds_read2_b32 v[212:213], v193 offset0:36 offset1:101
	ds_read2_b32 v[214:215], v193 offset0:166 offset1:231
	ds_read2_b32 v[216:217], v192 offset0:40 offset1:105
	ds_read2_b32 v[218:219], v192 offset0:170 offset1:235
	ds_read2_b32 v[220:221], v193 offset0:44 offset1:109
	ds_read2_b32 v[222:223], v193 offset0:174 offset1:239
	s_waitcnt lgkmcnt(4)
	v_cvt_pk_bf16_f32 v200, v208, v209
	v_cvt_pk_bf16_f32 v201, v210, v211
	v_cvt_pk_bf16_f32 v202, v212, v213
	v_cvt_pk_bf16_f32 v203, v214, v215
	global_store_dwordx4 v197, v[200:203], s[20:21]
	v_add_u32_e32 v197, 0x8000, v197
	s_waitcnt lgkmcnt(0)
	v_cvt_pk_bf16_f32 v204, v216, v217
	v_cvt_pk_bf16_f32 v205, v218, v219
	v_cvt_pk_bf16_f32 v206, v220, v221
	v_cvt_pk_bf16_f32 v207, v222, v223
	global_store_dwordx4 v197, v[204:207], s[20:21]
	v_add_u32_e32 v197, 0x8000, v197
	ds_read2_b32 v[208:209], v192 offset0:48 offset1:113
	ds_read2_b32 v[210:211], v192 offset0:178 offset1:243
	ds_read2_b32 v[212:213], v193 offset0:52 offset1:117
	ds_read2_b32 v[214:215], v193 offset0:182 offset1:247
	ds_read2_b32 v[216:217], v192 offset0:56 offset1:121
	ds_read2_b32 v[218:219], v192 offset0:186 offset1:251
	ds_read2_b32 v[220:221], v193 offset0:60 offset1:125
	ds_read2_b32 v[222:223], v193 offset0:190 offset1:255
	s_waitcnt lgkmcnt(4)
	v_cvt_pk_bf16_f32 v200, v208, v209
	v_cvt_pk_bf16_f32 v201, v210, v211
	v_cvt_pk_bf16_f32 v202, v212, v213
	v_cvt_pk_bf16_f32 v203, v214, v215
	global_store_dwordx4 v197, v[200:203], s[20:21]
	v_add_u32_e32 v197, 0x8000, v197
	s_waitcnt lgkmcnt(0)
	v_cvt_pk_bf16_f32 v204, v216, v217
	v_cvt_pk_bf16_f32 v205, v218, v219
	v_cvt_pk_bf16_f32 v206, v220, v221
	v_cvt_pk_bf16_f32 v207, v222, v223
	global_store_dwordx4 v197, v[204:207], s[20:21]
	v_add_u32_e32 v197, 0x8000, v197
	s_waitcnt lgkmcnt(0)
	s_waitcnt vmcnt(23)
	v_mul_f32_e32 v64, v64, v160
	v_mul_f32_e32 v65, v65, v160
	v_mul_f32_e32 v66, v66, v160
	v_mul_f32_e32 v67, v67, v160
	ds_write2_b32 v176, v64, v65 offset1:1
	ds_write2_b32 v176, v66, v67 offset0:2 offset1:3
	s_waitcnt vmcnt(22)
	v_mul_f32_e32 v68, v68, v161
	v_mul_f32_e32 v69, v69, v161
	v_mul_f32_e32 v70, v70, v161
	v_mul_f32_e32 v71, v71, v161
	ds_write2_b32 v177, v68, v69 offset1:1
	ds_write2_b32 v177, v70, v71 offset0:2 offset1:3
	s_waitcnt vmcnt(21)
	v_mul_f32_e32 v72, v72, v162
	v_mul_f32_e32 v73, v73, v162
	v_mul_f32_e32 v74, v74, v162
	v_mul_f32_e32 v75, v75, v162
	ds_write2_b32 v178, v72, v73 offset1:1
	ds_write2_b32 v178, v74, v75 offset0:2 offset1:3
	s_waitcnt vmcnt(20)
	v_mul_f32_e32 v76, v76, v163
	v_mul_f32_e32 v77, v77, v163
	v_mul_f32_e32 v78, v78, v163
	v_mul_f32_e32 v79, v79, v163
	ds_write2_b32 v179, v76, v77 offset1:1
	ds_write2_b32 v179, v78, v79 offset0:2 offset1:3
	s_waitcnt vmcnt(19)
	v_mul_f32_e32 v80, v80, v164
	v_mul_f32_e32 v81, v81, v164
	v_mul_f32_e32 v82, v82, v164
	v_mul_f32_e32 v83, v83, v164
	ds_write2_b32 v180, v80, v81 offset1:1
	ds_write2_b32 v180, v82, v83 offset0:2 offset1:3
	s_waitcnt vmcnt(18)
	v_mul_f32_e32 v84, v84, v165
	v_mul_f32_e32 v85, v85, v165
	v_mul_f32_e32 v86, v86, v165
	v_mul_f32_e32 v87, v87, v165
	ds_write2_b32 v181, v84, v85 offset1:1
	ds_write2_b32 v181, v86, v87 offset0:2 offset1:3
	s_waitcnt vmcnt(17)
	v_mul_f32_e32 v88, v88, v166
	v_mul_f32_e32 v89, v89, v166
	v_mul_f32_e32 v90, v90, v166
	v_mul_f32_e32 v91, v91, v166
	ds_write2_b32 v182, v88, v89 offset1:1
	ds_write2_b32 v182, v90, v91 offset0:2 offset1:3
	s_waitcnt vmcnt(16)
	v_mul_f32_e32 v92, v92, v167
	v_mul_f32_e32 v93, v93, v167
	v_mul_f32_e32 v94, v94, v167
	v_mul_f32_e32 v95, v95, v167
	ds_write2_b32 v183, v92, v93 offset1:1
	ds_write2_b32 v183, v94, v95 offset0:2 offset1:3
	s_waitcnt vmcnt(15)
	v_mul_f32_e32 v96, v96, v168
	v_mul_f32_e32 v97, v97, v168
	v_mul_f32_e32 v98, v98, v168
	v_mul_f32_e32 v99, v99, v168
	ds_write2_b32 v184, v96, v97 offset1:1
	ds_write2_b32 v184, v98, v99 offset0:2 offset1:3
	s_waitcnt vmcnt(14)
	v_mul_f32_e32 v100, v100, v169
	v_mul_f32_e32 v101, v101, v169
	v_mul_f32_e32 v102, v102, v169
	v_mul_f32_e32 v103, v103, v169
	ds_write2_b32 v185, v100, v101 offset1:1
	ds_write2_b32 v185, v102, v103 offset0:2 offset1:3
	s_waitcnt vmcnt(13)
	v_mul_f32_e32 v104, v104, v170
	v_mul_f32_e32 v105, v105, v170
	v_mul_f32_e32 v106, v106, v170
	v_mul_f32_e32 v107, v107, v170
	ds_write2_b32 v186, v104, v105 offset1:1
	ds_write2_b32 v186, v106, v107 offset0:2 offset1:3
	s_waitcnt vmcnt(12)
	v_mul_f32_e32 v108, v108, v171
	v_mul_f32_e32 v109, v109, v171
	v_mul_f32_e32 v110, v110, v171
	v_mul_f32_e32 v111, v111, v171
	ds_write2_b32 v187, v108, v109 offset1:1
	ds_write2_b32 v187, v110, v111 offset0:2 offset1:3
	s_waitcnt vmcnt(11)
	v_mul_f32_e32 v112, v112, v172
	v_mul_f32_e32 v113, v113, v172
	v_mul_f32_e32 v114, v114, v172
	v_mul_f32_e32 v115, v115, v172
	ds_write2_b32 v188, v112, v113 offset1:1
	ds_write2_b32 v188, v114, v115 offset0:2 offset1:3
	s_waitcnt vmcnt(10)
	v_mul_f32_e32 v116, v116, v173
	v_mul_f32_e32 v117, v117, v173
	v_mul_f32_e32 v118, v118, v173
	v_mul_f32_e32 v119, v119, v173
	ds_write2_b32 v189, v116, v117 offset1:1
	ds_write2_b32 v189, v118, v119 offset0:2 offset1:3
	s_waitcnt vmcnt(9)
	v_mul_f32_e32 v120, v120, v174
	v_mul_f32_e32 v121, v121, v174
	v_mul_f32_e32 v122, v122, v174
	v_mul_f32_e32 v123, v123, v174
	ds_write2_b32 v190, v120, v121 offset1:1
	ds_write2_b32 v190, v122, v123 offset0:2 offset1:3
	s_waitcnt vmcnt(8)
	v_mul_f32_e32 v124, v124, v175
	v_mul_f32_e32 v125, v125, v175
	v_mul_f32_e32 v126, v126, v175
	v_mul_f32_e32 v127, v127, v175
	ds_write2_b32 v191, v124, v125 offset1:1
	ds_write2_b32 v191, v126, v127 offset0:2 offset1:3
	s_waitcnt lgkmcnt(0)
	v_mov_b32_e32 v197, v196
	ds_read2_b32 v[208:209], v192 offset0:0 offset1:65
	ds_read2_b32 v[210:211], v192 offset0:130 offset1:195
	ds_read2_b32 v[212:213], v193 offset0:4 offset1:69
	ds_read2_b32 v[214:215], v193 offset0:134 offset1:199
	ds_read2_b32 v[216:217], v192 offset0:8 offset1:73
	ds_read2_b32 v[218:219], v192 offset0:138 offset1:203
	ds_read2_b32 v[220:221], v193 offset0:12 offset1:77
	ds_read2_b32 v[222:223], v193 offset0:142 offset1:207
	s_waitcnt lgkmcnt(4)
	v_cvt_pk_bf16_f32 v200, v208, v209
	v_cvt_pk_bf16_f32 v201, v210, v211
	v_cvt_pk_bf16_f32 v202, v212, v213
	v_cvt_pk_bf16_f32 v203, v214, v215
	global_store_dwordx4 v197, v[200:203], s[26:27]
	v_add_u32_e32 v197, 0x8000, v197
	s_waitcnt lgkmcnt(0)
	v_cvt_pk_bf16_f32 v204, v216, v217
	v_cvt_pk_bf16_f32 v205, v218, v219
	v_cvt_pk_bf16_f32 v206, v220, v221
	v_cvt_pk_bf16_f32 v207, v222, v223
	global_store_dwordx4 v197, v[204:207], s[26:27]
	v_add_u32_e32 v197, 0x8000, v197
	ds_read2_b32 v[208:209], v192 offset0:16 offset1:81
	ds_read2_b32 v[210:211], v192 offset0:146 offset1:211
	ds_read2_b32 v[212:213], v193 offset0:20 offset1:85
	ds_read2_b32 v[214:215], v193 offset0:150 offset1:215
	ds_read2_b32 v[216:217], v192 offset0:24 offset1:89
	ds_read2_b32 v[218:219], v192 offset0:154 offset1:219
	ds_read2_b32 v[220:221], v193 offset0:28 offset1:93
	ds_read2_b32 v[222:223], v193 offset0:158 offset1:223
	s_waitcnt lgkmcnt(4)
	v_cvt_pk_bf16_f32 v200, v208, v209
	v_cvt_pk_bf16_f32 v201, v210, v211
	v_cvt_pk_bf16_f32 v202, v212, v213
	v_cvt_pk_bf16_f32 v203, v214, v215
	global_store_dwordx4 v197, v[200:203], s[26:27]
	v_add_u32_e32 v197, 0x8000, v197
	s_waitcnt lgkmcnt(0)
	v_cvt_pk_bf16_f32 v204, v216, v217
	v_cvt_pk_bf16_f32 v205, v218, v219
	v_cvt_pk_bf16_f32 v206, v220, v221
	v_cvt_pk_bf16_f32 v207, v222, v223
	global_store_dwordx4 v197, v[204:207], s[26:27]
	v_add_u32_e32 v197, 0x8000, v197
	ds_read2_b32 v[208:209], v192 offset0:32 offset1:97
	ds_read2_b32 v[210:211], v192 offset0:162 offset1:227
	ds_read2_b32 v[212:213], v193 offset0:36 offset1:101
	ds_read2_b32 v[214:215], v193 offset0:166 offset1:231
	ds_read2_b32 v[216:217], v192 offset0:40 offset1:105
	ds_read2_b32 v[218:219], v192 offset0:170 offset1:235
	ds_read2_b32 v[220:221], v193 offset0:44 offset1:109
	ds_read2_b32 v[222:223], v193 offset0:174 offset1:239
	s_waitcnt lgkmcnt(4)
	v_cvt_pk_bf16_f32 v200, v208, v209
	v_cvt_pk_bf16_f32 v201, v210, v211
	v_cvt_pk_bf16_f32 v202, v212, v213
	v_cvt_pk_bf16_f32 v203, v214, v215
	global_store_dwordx4 v197, v[200:203], s[26:27]
	v_add_u32_e32 v197, 0x8000, v197
	s_waitcnt lgkmcnt(0)
	v_cvt_pk_bf16_f32 v204, v216, v217
	v_cvt_pk_bf16_f32 v205, v218, v219
	v_cvt_pk_bf16_f32 v206, v220, v221
	v_cvt_pk_bf16_f32 v207, v222, v223
	global_store_dwordx4 v197, v[204:207], s[26:27]
	v_add_u32_e32 v197, 0x8000, v197
	ds_read2_b32 v[208:209], v192 offset0:48 offset1:113
	ds_read2_b32 v[210:211], v192 offset0:178 offset1:243
	ds_read2_b32 v[212:213], v193 offset0:52 offset1:117
	ds_read2_b32 v[214:215], v193 offset0:182 offset1:247
	ds_read2_b32 v[216:217], v192 offset0:56 offset1:121
	ds_read2_b32 v[218:219], v192 offset0:186 offset1:251
	ds_read2_b32 v[220:221], v193 offset0:60 offset1:125
	ds_read2_b32 v[222:223], v193 offset0:190 offset1:255
	s_waitcnt lgkmcnt(4)
	v_cvt_pk_bf16_f32 v200, v208, v209
	v_cvt_pk_bf16_f32 v201, v210, v211
	v_cvt_pk_bf16_f32 v202, v212, v213
	v_cvt_pk_bf16_f32 v203, v214, v215
	global_store_dwordx4 v197, v[200:203], s[26:27]
	v_add_u32_e32 v197, 0x8000, v197
	s_waitcnt lgkmcnt(0)
	v_cvt_pk_bf16_f32 v204, v216, v217
	v_cvt_pk_bf16_f32 v205, v218, v219
	v_cvt_pk_bf16_f32 v206, v220, v221
	v_cvt_pk_bf16_f32 v207, v222, v223
	global_store_dwordx4 v197, v[204:207], s[26:27]
	v_add_u32_e32 v197, 0x8000, v197
.Lmy_wup_end:
	s_cmp_eq_u32 s94, 0
	s_cbranch_scc0 .Lmy_p2_done
	s_mov_b32 s94, 1
	s_waitcnt vmcnt(0) lgkmcnt(0)
	s_branch .Lmy_p2_pre
